# u8 with gate prefetch issued after first staging + cross-attention key-norm gains parked in LDS once per tile (ds_read instead of 8 global loads per kv head)
# speedup vs baseline: 1.0200x; 1.0002x over previous
.LBB0_208:
	s_waitcnt vmcnt(0)
	v_lshlrev_b32_e32 v2, 1, v111
	v_lshl_add_u64 v[14:15], v[82:83], 0, v[2:3]
	global_load_dwordx2 v[20:21], v[14:15], off offset:3072
	v_readlane_b32 s8, v244, 0
	v_lshlrev_b32_e32 v18, 2, v111
	v_readlane_b32 s12, v244, 4
	v_readlane_b32 s13, v244, 5
	v_mov_b32_e32 v16, v110
	s_nop 1
	v_permlane16_swap_b32 v16, v110
	v_readlane_b32 s4, v244, 57
	v_lshlrev_b64 v[12:13], 11, v[80:81]
	v_readlane_b32 s6, v244, 59
	v_readlane_b32 s7, v244, 60
	global_load_dwordx4 v[8:11], v18, s[12:13] offset:2048
	global_load_dwordx2 v[46:47], v[14:15], off offset:3104
	global_load_dwordx2 v[52:53], v[14:15], off offset:3136
	global_load_dwordx2 v[54:55], v[14:15], off offset:3168
	global_load_dwordx4 v[56:59], v18, s[12:13] offset:2112
	global_load_dwordx4 v[60:63], v18, s[12:13] offset:2176
	global_load_dwordx4 v[64:67], v18, s[12:13] offset:2240
	global_load_dwordx2 v[68:69], v[14:15], off offset:3200
	global_load_dwordx4 v[70:73], v18, s[12:13] offset:2304
	global_load_dwordx2 v[74:75], v[14:15], off offset:3232
	global_load_dwordx2 v[76:77], v[14:15], off offset:3264
	global_load_dwordx2 v[78:79], v[14:15], off offset:3296
	global_load_dwordx4 v[84:87], v18, s[12:13] offset:2368
	global_load_dwordx4 v[88:91], v18, s[12:13] offset:2432
	global_load_dwordx4 v[92:95], v18, s[12:13] offset:2496
	global_load_dwordx2 v[96:97], v[14:15], off offset:3328
	global_load_dwordx4 v[98:101], v18, s[12:13] offset:2560
	global_load_dwordx2 v[102:103], v[14:15], off offset:3360
	global_load_dwordx2 v[104:105], v[14:15], off offset:3392
	global_load_dwordx2 v[106:107], v[14:15], off offset:3424
	global_load_dwordx4 v[116:119], v18, s[12:13] offset:2624
	global_load_dwordx4 v[120:123], v18, s[12:13] offset:2688
	global_load_dwordx4 v[124:127], v18, s[12:13] offset:2752
	global_load_dwordx2 v[132:133], v[14:15], off offset:3456
	global_load_dwordx4 v[134:137], v18, s[12:13] offset:2816
	global_load_dwordx2 v[138:139], v[14:15], off offset:3488
	global_load_dwordx2 v[140:141], v[14:15], off offset:3520
	global_load_dwordx2 v[142:143], v[14:15], off offset:3552
	global_load_dwordx4 v[144:147], v18, s[12:13] offset:2880
	global_load_dwordx4 v[148:151], v18, s[12:13] offset:2944
	global_load_dwordx4 v[152:155], v18, s[12:13] offset:3008
	v_readlane_b32 s32, v244, 2
	v_readlane_b32 s33, v244, 3
	v_readlane_b32 s24, v243, 8
	v_readlane_b32 s26, v244, 50
	v_readlane_b32 s27, v244, 51
	v_readlane_b32 s28, v243, 30
	v_readlane_b32 s30, v243, 5
	v_readlane_b32 s31, v243, 6
	v_lshrrev_b32_e32 v108, 1, v0
	v_and_b32_e32 v129, 1, v0
	v_and_b32_e32 v168, 15, v0
	v_lshrrev_b32_e32 v169, 6, v0
	v_lshl_add_u32 v108, s24, 8, v108
	v_lshlrev_b32_e32 v129, 6, v129
	v_or_b32_e32 v168, s28, v168
	v_lshl_add_u32 v108, v108, 10, v129
	v_lshl_add_u32 v168, v169, 4, v168
	v_bfe_u32 v169, v0, 4, 2
	v_mul_u32_u24_e32 v168, 0x1200, v168
	v_lshl_add_u32 v168, v169, 4, v168
	global_load_dwordx4 v[156:159], v108, s[26:27] offset:48
	global_load_dwordx4 v[160:163], v108, s[26:27] offset:32
	global_load_dwordx4 v[164:167], v108, s[26:27] offset:16
	global_load_dwordx4 v[172:175], v108, s[26:27]
	global_load_dwordx4 v[176:179], v108, s[26:27] offset:512
	global_load_dwordx4 v[196:199], v108, s[26:27] offset:528
	global_load_dwordx4 v[200:203], v108, s[26:27] offset:544
	global_load_dwordx4 v[204:207], v108, s[26:27] offset:560
	global_load_dwordx4 v[208:211], v168, s[30:31] offset:3584
	global_load_dwordx4 v[212:215], v168, s[30:31] offset:3648
	v_and_b32_e32 v195, 63, v0
	v_lshlrev_b32_e32 v195, 2, v195
	global_load_dword v195, v195, s[32:33]
	s_waitcnt lgkmcnt(0)
	v_add_f32_e32 v19, v110, v16
	v_mov_b32_e32 v28, v19
	s_nop 1
	v_permlane32_swap_b32 v28, v19
	s_mov_b64 s[0:1], 0xdde0400
	v_lshl_add_u64 v[12:13], s[6:7], 0, v[12:13]
	v_lshl_add_u64 v[12:13], v[12:13], 0, s[0:1]
	s_mov_b32 s0, 0x800000
	s_waitcnt lgkmcnt(0)
	v_add_f32_e32 v19, v19, v28
	v_fmamk_f32 v19, v19, 0x3b800000, v180
	v_mul_f32_e32 v28, 0x4b800000, v19
	v_cmp_gt_f32_e32 vcc, s0, v19
	ds_read2_b64 v[4:7], v109 offset1:4
	v_cndmask_b32_e32 v19, v19, v28, vcc
	v_rsq_f32_e32 v19, v19
	v_lshl_add_u64 v[26:27], v[12:13], 0, v[2:3]
	s_waitcnt lgkmcnt(0)
	v_lshlrev_b32_e32 v29, 16, v4
	v_and_b32_e32 v31, 0xffff0000, v4
	v_mul_f32_e32 v4, 0x45800000, v19
	v_lshlrev_b32_e32 v33, 16, v5
	v_and_b32_e32 v35, 0xffff0000, v5
	v_cndmask_b32_e32 v5, v19, v4, vcc
	v_mov_b32_e32 v38, v5
	v_mov_b32_e32 v40, v5
	v_mov_b32_e32 v42, v5
	v_readlane_b32 s88, v243, 5
	v_readlane_b32 s20, v243, 30
	v_readlane_b32 s89, v243, 6
	v_readlane_b32 s0, v243, 8
	v_mov_b32_e32 v45, v3
	v_mov_b32_e32 v115, v3
	v_readlane_b32 s2, v244, 62
	v_readlane_b32 s10, v244, 2
	v_readlane_b32 s11, v244, 3
	v_mov_b32_e32 v51, v3
	v_readlane_b32 s9, v244, 1
	v_readlane_b32 s3, v244, 63
	v_readlane_b32 s14, v244, 6
	v_readlane_b32 s15, v244, 7
	v_readlane_b32 s5, v244, 58
	v_readlane_b32 s86, v243, 3
	v_readlane_b32 s22, v243, 28
	v_mov_b32_e32 v130, 0
	s_mov_b64 s[4:5], 0
	v_readlane_b32 s58, v243, 2
	v_readlane_b32 s87, v243, 4
	s_movk_i32 s84, 0x7f
	v_readlane_b32 s23, v243, 29
	v_readlane_b32 s21, v243, 31
	s_waitcnt vmcnt(42)
	v_lshlrev_b32_e32 v28, 16, v20
	v_mul_f32_e32 v4, 0xbfb8aa3b, v28
	v_exp_f32_e32 v4, v4
	v_and_b32_e32 v30, 0xffff0000, v20
	v_mul_f32_e32 v19, 0xbfb8aa3b, v30
	v_exp_f32_e32 v19, v19
	v_add_f32_e32 v4, 1.0, v4
	v_rcp_f32_e32 v4, v4
	v_lshlrev_b32_e32 v32, 16, v21
	v_and_b32_e32 v34, 0xffff0000, v21
	v_mul_f32_e32 v20, 0xbfb8aa3b, v32
	v_mul_f32_e32 v21, 0xbfb8aa3b, v34
	v_exp_f32_e32 v36, v20
	v_add_f32_e32 v19, 1.0, v19
	v_exp_f32_e32 v37, v21
	v_pk_mul_f32 v[20:21], v[4:5], v[28:29]
	v_rcp_f32_e32 v4, v19
	v_add_f32_e32 v19, 1.0, v36
	s_waitcnt vmcnt(41)
	v_mul_f32_e32 v8, v8, v21
	v_add_f32_e32 v36, 1.0, v37
	v_pk_mul_f32 v[28:29], v[4:5], v[30:31]
	v_rcp_f32_e32 v4, v19
	v_mul_f32_e32 v19, v20, v8
	v_mul_f32_e32 v8, v9, v29
	v_mul_f32_e32 v20, v28, v8
	v_pk_mul_f32 v[8:9], v[4:5], v[32:33]
	v_rcp_f32_e32 v4, v36
	v_mul_f32_e32 v9, v10, v9
	v_mul_f32_e32 v10, v8, v9
	v_cvt_pk_bf16_f32 v20, v19, v20
	v_pk_mul_f32 v[8:9], v[4:5], v[34:35]
	v_lshlrev_b32_e32 v28, 16, v7
	v_mul_f32_e32 v4, v11, v9
	v_mul_f32_e32 v4, v8, v4
	v_cvt_pk_bf16_f32 v21, v10, v4
	global_store_dwordx2 v[26:27], v[20:21], off
	v_and_b32_e32 v30, 0xffff0000, v7
	s_waitcnt vmcnt(41)
	v_lshlrev_b32_e32 v27, 16, v46
	v_and_b32_e32 v7, 0xffff0000, v46
	v_lshlrev_b32_e32 v29, 16, v47
	v_and_b32_e32 v31, 0xffff0000, v47
	v_mul_f32_e32 v4, 0xbfb8aa3b, v27
	v_mul_f32_e32 v19, 0xbfb8aa3b, v7
	v_mul_f32_e32 v22, 0xbfb8aa3b, v29
	v_mul_f32_e32 v23, 0xbfb8aa3b, v31
	v_exp_f32_e32 v4, v4
	v_exp_f32_e32 v19, v19
	v_exp_f32_e32 v22, v22
	v_exp_f32_e32 v23, v23
	v_add_f32_e32 v4, 1.0, v4
	v_add_f32_e32 v19, 1.0, v19
	v_add_f32_e32 v22, 1.0, v22
	v_add_f32_e32 v23, 1.0, v23
	v_rcp_f32_e32 v33, v4
	v_rcp_f32_e32 v35, v19
	v_rcp_f32_e32 v37, v22
	v_rcp_f32_e32 v39, v23
	v_lshlrev_b32_e32 v26, 16, v6
	v_and_b32_e32 v6, 0xffff0000, v6
	v_mov_b32_e32 v32, v5
	v_mov_b32_e32 v34, v5
	v_mov_b32_e32 v36, v5
	v_pk_mul_f32 v[22:23], v[32:33], v[26:27]
	v_pk_mul_f32 v[6:7], v[34:35], v[6:7]
	v_pk_mul_f32 v[26:27], v[36:37], v[28:29]
	v_mov_b32_e32 v21, v3
	v_or_b32_e32 v20, 32, v2
	v_pk_mul_f32 v[28:29], v[38:39], v[30:31]
	v_lshl_add_u64 v[20:21], v[12:13], 0, v[20:21]
	s_waitcnt vmcnt(40)
	v_and_b32_e32 v31, 0xffff0000, v53
	s_waitcnt vmcnt(38)
	v_mul_f32_e32 v4, v56, v22
	v_mul_f32_e32 v6, v57, v6
	v_mul_f32_e32 v8, v58, v26
	v_mul_f32_e32 v9, v59, v28
	v_mul_f32_e32 v6, v6, v7
	v_mul_f32_e32 v7, v8, v27
	v_mul_f32_e32 v4, v4, v23
	v_mul_f32_e32 v8, v9, v29
	v_cvt_pk_bf16_f32 v6, v4, v6
	v_cvt_pk_bf16_f32 v7, v7, v8
	global_store_dwordx2 v[20:21], v[6:7], off
	ds_read2_b64 v[20:23], v109 offset0:8 offset1:12
	v_lshlrev_b32_e32 v27, 16, v52
	v_lshlrev_b32_e32 v29, 16, v53
	v_mul_f32_e32 v4, 0xbfb8aa3b, v27
	v_mul_f32_e32 v25, 0xbfb8aa3b, v31
	s_waitcnt lgkmcnt(0)
	v_lshlrev_b32_e32 v28, 16, v21
	v_and_b32_e32 v30, 0xffff0000, v21
	v_and_b32_e32 v21, 0xffff0000, v52
	v_mul_f32_e32 v19, 0xbfb8aa3b, v21
	v_mul_f32_e32 v24, 0xbfb8aa3b, v29
	v_exp_f32_e32 v4, v4
	v_exp_f32_e32 v19, v19
	v_exp_f32_e32 v24, v24
	v_exp_f32_e32 v25, v25
	v_add_f32_e32 v4, 1.0, v4
	v_add_f32_e32 v19, 1.0, v19
	v_add_f32_e32 v24, 1.0, v24
	v_add_f32_e32 v25, 1.0, v25
	v_rcp_f32_e32 v33, v4
	v_rcp_f32_e32 v35, v19
	v_rcp_f32_e32 v37, v24
	v_rcp_f32_e32 v39, v25
	v_lshlrev_b32_e32 v26, 16, v20
	v_and_b32_e32 v20, 0xffff0000, v20
	v_pk_mul_f32 v[24:25], v[32:33], v[26:27]
	v_pk_mul_f32 v[20:21], v[34:35], v[20:21]
	v_pk_mul_f32 v[26:27], v[36:37], v[28:29]
	v_mov_b32_e32 v11, v3
	v_or_b32_e32 v10, 64, v2
	v_pk_mul_f32 v[28:29], v[38:39], v[30:31]
	v_lshl_add_u64 v[10:11], v[12:13], 0, v[10:11]
	v_mov_b32_e32 v30, v5
	s_waitcnt vmcnt(38)
	v_mul_f32_e32 v4, v60, v24
	v_mul_f32_e32 v6, v61, v20
	v_mul_f32_e32 v7, v62, v26
	v_mul_f32_e32 v8, v63, v28
	v_mul_f32_e32 v6, v6, v21
	v_mul_f32_e32 v7, v7, v27
	v_mul_f32_e32 v4, v4, v25
	v_mul_f32_e32 v8, v8, v29
	v_cvt_pk_bf16_f32 v6, v4, v6
	v_cvt_pk_bf16_f32 v7, v7, v8
	global_store_dwordx2 v[10:11], v[6:7], off
	v_lshlrev_b32_e32 v26, 16, v23
	v_and_b32_e32 v28, 0xffff0000, v23
	v_lshlrev_b32_e32 v21, 16, v54
	v_and_b32_e32 v23, 0xffff0000, v54
	v_lshlrev_b32_e32 v27, 16, v55
	v_and_b32_e32 v29, 0xffff0000, v55
	v_mul_f32_e32 v4, 0xbfb8aa3b, v21
	v_mul_f32_e32 v16, 0xbfb8aa3b, v23
	v_mul_f32_e32 v17, 0xbfb8aa3b, v27
	v_mul_f32_e32 v19, 0xbfb8aa3b, v29
	v_exp_f32_e32 v4, v4
	v_exp_f32_e32 v16, v16
	v_exp_f32_e32 v17, v17
	v_exp_f32_e32 v19, v19
	v_add_f32_e32 v4, 1.0, v4
	v_add_f32_e32 v16, 1.0, v16
	v_add_f32_e32 v17, 1.0, v17
	v_add_f32_e32 v19, 1.0, v19
	v_rcp_f32_e32 v31, v4
	v_rcp_f32_e32 v33, v16
	v_rcp_f32_e32 v35, v17
	v_rcp_f32_e32 v37, v19
	v_lshlrev_b32_e32 v20, 16, v22
	v_and_b32_e32 v22, 0xffff0000, v22
	v_pk_mul_f32 v[16:17], v[30:31], v[20:21]
	v_pk_mul_f32 v[20:21], v[32:33], v[22:23]
	v_pk_mul_f32 v[22:23], v[34:35], v[26:27]
	v_mov_b32_e32 v11, v3
	v_or_b32_e32 v10, 0x60, v2
	v_pk_mul_f32 v[26:27], v[36:37], v[28:29]
	v_lshl_add_u64 v[10:11], v[12:13], 0, v[10:11]
	s_waitcnt vmcnt(38)
	v_mul_f32_e32 v4, v64, v16
	v_mul_f32_e32 v6, v65, v20
	v_mul_f32_e32 v7, v66, v22
	v_mul_f32_e32 v8, v67, v26
	v_mul_f32_e32 v6, v6, v21
	v_mul_f32_e32 v7, v7, v23
	v_mul_f32_e32 v4, v4, v17
	v_mul_f32_e32 v8, v8, v27
	v_cvt_pk_bf16_f32 v6, v4, v6
	v_cvt_pk_bf16_f32 v7, v7, v8
	global_store_dwordx2 v[10:11], v[6:7], off
	ds_read2_b64 v[20:23], v109 offset0:16 offset1:20
	s_waitcnt vmcnt(38)
	v_lshlrev_b32_e32 v31, 16, v68
	v_lshlrev_b32_e32 v33, 16, v69
	v_and_b32_e32 v35, 0xffff0000, v69
	s_waitcnt lgkmcnt(0)
	v_lshlrev_b32_e32 v32, 16, v21
	v_and_b32_e32 v34, 0xffff0000, v21
	v_and_b32_e32 v21, 0xffff0000, v68
	v_mul_f32_e32 v4, 0xbfb8aa3b, v31
	v_mul_f32_e32 v19, 0xbfb8aa3b, v21
	v_mul_f32_e32 v24, 0xbfb8aa3b, v33
	v_mul_f32_e32 v25, 0xbfb8aa3b, v35
	v_exp_f32_e32 v4, v4
	v_exp_f32_e32 v19, v19
	v_exp_f32_e32 v24, v24
	v_exp_f32_e32 v25, v25
	v_add_f32_e32 v4, 1.0, v4
	v_add_f32_e32 v19, 1.0, v19
	v_add_f32_e32 v24, 1.0, v24
	v_add_f32_e32 v25, 1.0, v25
	v_rcp_f32_e32 v37, v4
	v_rcp_f32_e32 v39, v19
	v_rcp_f32_e32 v41, v24
	v_rcp_f32_e32 v43, v25
	v_lshlrev_b32_e32 v30, 16, v20
	v_and_b32_e32 v20, 0xffff0000, v20
	v_pk_mul_f32 v[24:25], v[36:37], v[30:31]
	v_pk_mul_f32 v[20:21], v[38:39], v[20:21]
	v_pk_mul_f32 v[30:31], v[40:41], v[32:33]
	v_mov_b32_e32 v17, v3
	v_or_b32_e32 v16, 0x80, v2
	v_pk_mul_f32 v[32:33], v[42:43], v[34:35]
	v_lshl_add_u64 v[16:17], v[12:13], 0, v[16:17]
	v_mov_b32_e32 v34, v5
	s_waitcnt vmcnt(37)
	v_mul_f32_e32 v4, v70, v24
	v_mul_f32_e32 v8, v71, v20
	v_mul_f32_e32 v9, v72, v30
	v_mul_f32_e32 v10, v73, v32
	v_mul_f32_e32 v8, v8, v21
	v_mul_f32_e32 v9, v9, v31
	v_mul_f32_e32 v4, v4, v25
	v_mul_f32_e32 v10, v10, v33
	v_cvt_pk_bf16_f32 v8, v4, v8
	v_cvt_pk_bf16_f32 v9, v9, v10
	global_store_dwordx2 v[16:17], v[8:9], off
	v_lshlrev_b32_e32 v24, 16, v23
	v_and_b32_e32 v30, 0xffff0000, v23
	s_waitcnt vmcnt(37)
	v_lshlrev_b32_e32 v21, 16, v74
	v_and_b32_e32 v23, 0xffff0000, v74
	v_lshlrev_b32_e32 v25, 16, v75
	v_and_b32_e32 v31, 0xffff0000, v75
	v_mul_f32_e32 v4, 0xbfb8aa3b, v21
	v_mul_f32_e32 v19, 0xbfb8aa3b, v23
	v_mul_f32_e32 v26, 0xbfb8aa3b, v25
	v_mul_f32_e32 v27, 0xbfb8aa3b, v31
	v_exp_f32_e32 v4, v4
	v_exp_f32_e32 v19, v19
	v_exp_f32_e32 v26, v26
	v_exp_f32_e32 v27, v27
	v_add_f32_e32 v4, 1.0, v4
	v_add_f32_e32 v19, 1.0, v19
	v_add_f32_e32 v26, 1.0, v26
	v_add_f32_e32 v27, 1.0, v27
	v_rcp_f32_e32 v33, v4
	v_rcp_f32_e32 v35, v19
	v_rcp_f32_e32 v37, v26
	v_rcp_f32_e32 v39, v27
	v_lshlrev_b32_e32 v20, 16, v22
	v_and_b32_e32 v22, 0xffff0000, v22
	v_mov_b32_e32 v32, v5
	v_pk_mul_f32 v[20:21], v[32:33], v[20:21]
	v_pk_mul_f32 v[22:23], v[34:35], v[22:23]
	v_pk_mul_f32 v[24:25], v[36:37], v[24:25]
	v_mov_b32_e32 v17, v3
	v_or_b32_e32 v16, 0xa0, v2
	v_pk_mul_f32 v[26:27], v[38:39], v[30:31]
	v_lshl_add_u64 v[16:17], v[12:13], 0, v[16:17]
	s_waitcnt vmcnt(36)
	v_and_b32_e32 v31, 0xffff0000, v77
	s_waitcnt vmcnt(34)
	v_mul_f32_e32 v4, v84, v20
	v_mul_f32_e32 v8, v85, v22
	v_mul_f32_e32 v9, v86, v24
	v_mul_f32_e32 v10, v87, v26
	v_mul_f32_e32 v8, v8, v23
	v_mul_f32_e32 v9, v9, v25
	v_mul_f32_e32 v4, v4, v21
	v_mul_f32_e32 v10, v10, v27
	v_cvt_pk_bf16_f32 v8, v4, v8
	v_cvt_pk_bf16_f32 v9, v9, v10
	global_store_dwordx2 v[16:17], v[8:9], off
	ds_read2_b64 v[20:23], v109 offset0:24 offset1:28
	v_lshlrev_b32_e32 v25, 16, v76
	v_lshlrev_b32_e32 v27, 16, v77
	v_mul_f32_e32 v4, 0xbfb8aa3b, v25
	v_mul_f32_e32 v29, 0xbfb8aa3b, v31
	s_waitcnt lgkmcnt(0)
	v_lshlrev_b32_e32 v26, 16, v21
	v_and_b32_e32 v30, 0xffff0000, v21
	v_and_b32_e32 v21, 0xffff0000, v76
	v_mul_f32_e32 v19, 0xbfb8aa3b, v21
	v_mul_f32_e32 v28, 0xbfb8aa3b, v27
	v_exp_f32_e32 v4, v4
	v_exp_f32_e32 v19, v19
	v_exp_f32_e32 v28, v28
	v_exp_f32_e32 v29, v29
	v_add_f32_e32 v4, 1.0, v4
	v_add_f32_e32 v19, 1.0, v19
	v_add_f32_e32 v28, 1.0, v28
	v_add_f32_e32 v29, 1.0, v29
	v_rcp_f32_e32 v33, v4
	v_rcp_f32_e32 v35, v19
	v_rcp_f32_e32 v37, v28
	v_rcp_f32_e32 v39, v29
	v_lshlrev_b32_e32 v24, 16, v20
	v_and_b32_e32 v20, 0xffff0000, v20
	v_pk_mul_f32 v[24:25], v[32:33], v[24:25]
	v_pk_mul_f32 v[20:21], v[34:35], v[20:21]
	v_pk_mul_f32 v[26:27], v[36:37], v[26:27]
	v_mov_b32_e32 v17, v3
	v_or_b32_e32 v16, 0xc0, v2
	v_pk_mul_f32 v[28:29], v[38:39], v[30:31]
	v_lshl_add_u64 v[16:17], v[12:13], 0, v[16:17]
	v_mov_b32_e32 v30, v5
	s_waitcnt vmcnt(34)
	v_mul_f32_e32 v4, v88, v24
	v_mul_f32_e32 v8, v89, v20
	v_mul_f32_e32 v9, v90, v26
	v_mul_f32_e32 v10, v91, v28
	v_mul_f32_e32 v8, v8, v21
	v_mul_f32_e32 v9, v9, v27
	v_mul_f32_e32 v4, v4, v25
	v_mul_f32_e32 v10, v10, v29
	v_cvt_pk_bf16_f32 v8, v4, v8
	v_cvt_pk_bf16_f32 v9, v9, v10
	global_store_dwordx2 v[16:17], v[8:9], off
	v_lshlrev_b32_e32 v26, 16, v23
	v_and_b32_e32 v28, 0xffff0000, v23
	v_lshlrev_b32_e32 v21, 16, v78
	v_and_b32_e32 v23, 0xffff0000, v78
	v_lshlrev_b32_e32 v27, 16, v79
	v_and_b32_e32 v29, 0xffff0000, v79
	v_mul_f32_e32 v4, 0xbfb8aa3b, v21
	v_mul_f32_e32 v6, 0xbfb8aa3b, v23
	v_mul_f32_e32 v7, 0xbfb8aa3b, v27
	v_mul_f32_e32 v19, 0xbfb8aa3b, v29
	v_exp_f32_e32 v4, v4
	v_exp_f32_e32 v6, v6
	v_exp_f32_e32 v7, v7
	v_exp_f32_e32 v19, v19
	v_add_f32_e32 v4, 1.0, v4
	v_add_f32_e32 v6, 1.0, v6
	v_add_f32_e32 v7, 1.0, v7
	v_add_f32_e32 v19, 1.0, v19
	v_rcp_f32_e32 v31, v4
	v_rcp_f32_e32 v33, v6
	v_rcp_f32_e32 v35, v7
	v_rcp_f32_e32 v37, v19
	v_lshlrev_b32_e32 v20, 16, v22
	v_and_b32_e32 v22, 0xffff0000, v22
	v_pk_mul_f32 v[6:7], v[30:31], v[20:21]
	v_pk_mul_f32 v[20:21], v[32:33], v[22:23]
	v_pk_mul_f32 v[22:23], v[34:35], v[26:27]
	v_mov_b32_e32 v17, v3
	v_or_b32_e32 v16, 0xe0, v2
	v_pk_mul_f32 v[26:27], v[36:37], v[28:29]
	v_lshl_add_u64 v[16:17], v[12:13], 0, v[16:17]
	s_waitcnt vmcnt(34)
	v_mul_f32_e32 v4, v92, v6
	v_mul_f32_e32 v6, v93, v20
	v_mul_f32_e32 v8, v94, v22
	v_mul_f32_e32 v9, v95, v26
	v_mul_f32_e32 v4, v4, v7
	v_mul_f32_e32 v6, v6, v21
	v_mul_f32_e32 v7, v8, v23
	v_mul_f32_e32 v8, v9, v27
	v_cvt_pk_bf16_f32 v6, v4, v6
	v_cvt_pk_bf16_f32 v7, v7, v8
	global_store_dwordx2 v[16:17], v[6:7], off
	ds_read2_b64 v[20:23], v109 offset0:32 offset1:36
	s_waitcnt vmcnt(34)
	v_lshlrev_b32_e32 v31, 16, v96
	v_lshlrev_b32_e32 v33, 16, v97
	v_and_b32_e32 v35, 0xffff0000, v97
	s_waitcnt lgkmcnt(0)
	v_lshlrev_b32_e32 v32, 16, v21
	v_and_b32_e32 v34, 0xffff0000, v21
	v_and_b32_e32 v21, 0xffff0000, v96
	v_mul_f32_e32 v4, 0xbfb8aa3b, v31
	v_mul_f32_e32 v19, 0xbfb8aa3b, v21
	v_mul_f32_e32 v24, 0xbfb8aa3b, v33
	v_mul_f32_e32 v25, 0xbfb8aa3b, v35
	v_exp_f32_e32 v4, v4
	v_exp_f32_e32 v19, v19
	v_exp_f32_e32 v24, v24
	v_exp_f32_e32 v25, v25
	v_add_f32_e32 v4, 1.0, v4
	v_add_f32_e32 v19, 1.0, v19
	v_add_f32_e32 v24, 1.0, v24
	v_add_f32_e32 v25, 1.0, v25
	v_rcp_f32_e32 v37, v4
	v_rcp_f32_e32 v39, v19
	v_rcp_f32_e32 v41, v24
	v_rcp_f32_e32 v43, v25
	v_lshlrev_b32_e32 v30, 16, v20
	v_and_b32_e32 v20, 0xffff0000, v20
	v_pk_mul_f32 v[24:25], v[36:37], v[30:31]
	v_pk_mul_f32 v[20:21], v[38:39], v[20:21]
	v_pk_mul_f32 v[30:31], v[40:41], v[32:33]
	v_mov_b32_e32 v17, v3
	v_or_b32_e32 v16, 0x100, v2
	v_pk_mul_f32 v[32:33], v[42:43], v[34:35]
	v_lshl_add_u64 v[16:17], v[12:13], 0, v[16:17]
	v_mov_b32_e32 v34, v5
	s_waitcnt vmcnt(33)
	v_mul_f32_e32 v4, v98, v24
	v_mul_f32_e32 v8, v99, v20
	v_mul_f32_e32 v9, v100, v30
	v_mul_f32_e32 v10, v101, v32
	v_mul_f32_e32 v8, v8, v21
	v_mul_f32_e32 v9, v9, v31
	v_mul_f32_e32 v4, v4, v25
	v_mul_f32_e32 v10, v10, v33
	v_cvt_pk_bf16_f32 v8, v4, v8
	v_cvt_pk_bf16_f32 v9, v9, v10
	global_store_dwordx2 v[16:17], v[8:9], off
	v_lshlrev_b32_e32 v24, 16, v23
	v_and_b32_e32 v30, 0xffff0000, v23
	s_waitcnt vmcnt(33)
	v_lshlrev_b32_e32 v21, 16, v102
	v_and_b32_e32 v23, 0xffff0000, v102
	v_lshlrev_b32_e32 v25, 16, v103
	v_and_b32_e32 v31, 0xffff0000, v103
	v_mul_f32_e32 v4, 0xbfb8aa3b, v21
	v_mul_f32_e32 v19, 0xbfb8aa3b, v23
	v_mul_f32_e32 v26, 0xbfb8aa3b, v25
	v_mul_f32_e32 v27, 0xbfb8aa3b, v31
	v_exp_f32_e32 v4, v4
	v_exp_f32_e32 v19, v19
	v_exp_f32_e32 v26, v26
	v_exp_f32_e32 v27, v27
	v_add_f32_e32 v4, 1.0, v4
	v_add_f32_e32 v19, 1.0, v19
	v_add_f32_e32 v26, 1.0, v26
	v_add_f32_e32 v27, 1.0, v27
	v_rcp_f32_e32 v33, v4
	v_rcp_f32_e32 v35, v19
	v_rcp_f32_e32 v37, v26
	v_rcp_f32_e32 v39, v27
	v_lshlrev_b32_e32 v20, 16, v22
	v_and_b32_e32 v22, 0xffff0000, v22
	v_mov_b32_e32 v32, v5
	v_pk_mul_f32 v[20:21], v[32:33], v[20:21]
	v_pk_mul_f32 v[22:23], v[34:35], v[22:23]
	v_pk_mul_f32 v[24:25], v[36:37], v[24:25]
	v_mov_b32_e32 v17, v3
	v_or_b32_e32 v16, 0x120, v2
	v_pk_mul_f32 v[26:27], v[38:39], v[30:31]
	v_lshl_add_u64 v[16:17], v[12:13], 0, v[16:17]
	s_waitcnt vmcnt(32)
	v_and_b32_e32 v31, 0xffff0000, v105
	s_waitcnt vmcnt(30)
	v_mul_f32_e32 v4, v116, v20
	v_mul_f32_e32 v8, v117, v22
	v_mul_f32_e32 v9, v118, v24
	v_mul_f32_e32 v10, v119, v26
	v_mul_f32_e32 v8, v8, v23
	v_mul_f32_e32 v9, v9, v25
	v_mul_f32_e32 v4, v4, v21
	v_mul_f32_e32 v10, v10, v27
	v_cvt_pk_bf16_f32 v8, v4, v8
	v_cvt_pk_bf16_f32 v9, v9, v10
	global_store_dwordx2 v[16:17], v[8:9], off
	ds_read2_b64 v[20:23], v109 offset0:40 offset1:44
	v_lshlrev_b32_e32 v25, 16, v104
	v_lshlrev_b32_e32 v27, 16, v105
	v_mul_f32_e32 v4, 0xbfb8aa3b, v25
	v_mul_f32_e32 v29, 0xbfb8aa3b, v31
	s_waitcnt lgkmcnt(0)
	v_lshlrev_b32_e32 v26, 16, v21
	v_and_b32_e32 v30, 0xffff0000, v21
	v_and_b32_e32 v21, 0xffff0000, v104
	v_mul_f32_e32 v19, 0xbfb8aa3b, v21
	v_mul_f32_e32 v28, 0xbfb8aa3b, v27
	v_exp_f32_e32 v4, v4
	v_exp_f32_e32 v19, v19
	v_exp_f32_e32 v28, v28
	v_exp_f32_e32 v29, v29
	v_add_f32_e32 v4, 1.0, v4
	v_add_f32_e32 v19, 1.0, v19
	v_add_f32_e32 v28, 1.0, v28
	v_add_f32_e32 v29, 1.0, v29
	v_rcp_f32_e32 v33, v4
	v_rcp_f32_e32 v35, v19
	v_rcp_f32_e32 v37, v28
	v_rcp_f32_e32 v39, v29
	v_lshlrev_b32_e32 v24, 16, v20
	v_and_b32_e32 v20, 0xffff0000, v20
	v_pk_mul_f32 v[24:25], v[32:33], v[24:25]
	v_pk_mul_f32 v[20:21], v[34:35], v[20:21]
	v_pk_mul_f32 v[26:27], v[36:37], v[26:27]
	v_mov_b32_e32 v17, v3
	v_or_b32_e32 v16, 0x140, v2
	v_pk_mul_f32 v[28:29], v[38:39], v[30:31]
	v_lshl_add_u64 v[16:17], v[12:13], 0, v[16:17]
	v_mov_b32_e32 v30, v5
	s_waitcnt vmcnt(30)
	v_mul_f32_e32 v4, v120, v24
	v_mul_f32_e32 v8, v121, v20
	v_mul_f32_e32 v9, v122, v26
	v_mul_f32_e32 v10, v123, v28
	v_mul_f32_e32 v8, v8, v21
	v_mul_f32_e32 v9, v9, v27
	v_mul_f32_e32 v4, v4, v25
	v_mul_f32_e32 v10, v10, v29
	v_cvt_pk_bf16_f32 v8, v4, v8
	v_cvt_pk_bf16_f32 v9, v9, v10
	global_store_dwordx2 v[16:17], v[8:9], off
	v_lshlrev_b32_e32 v26, 16, v23
	v_and_b32_e32 v28, 0xffff0000, v23
	v_lshlrev_b32_e32 v21, 16, v106
	v_and_b32_e32 v23, 0xffff0000, v106
	v_lshlrev_b32_e32 v27, 16, v107
	v_and_b32_e32 v29, 0xffff0000, v107
	v_mul_f32_e32 v4, 0xbfb8aa3b, v21
	v_mul_f32_e32 v6, 0xbfb8aa3b, v23
	v_mul_f32_e32 v7, 0xbfb8aa3b, v27
	v_mul_f32_e32 v19, 0xbfb8aa3b, v29
	v_exp_f32_e32 v4, v4
	v_exp_f32_e32 v6, v6
	v_exp_f32_e32 v7, v7
	v_exp_f32_e32 v19, v19
	v_add_f32_e32 v4, 1.0, v4
	v_add_f32_e32 v6, 1.0, v6
	v_add_f32_e32 v7, 1.0, v7
	v_add_f32_e32 v19, 1.0, v19
	v_rcp_f32_e32 v31, v4
	v_rcp_f32_e32 v33, v6
	v_rcp_f32_e32 v35, v7
	v_rcp_f32_e32 v37, v19
	v_lshlrev_b32_e32 v20, 16, v22
	v_and_b32_e32 v22, 0xffff0000, v22
	v_pk_mul_f32 v[6:7], v[30:31], v[20:21]
	v_pk_mul_f32 v[20:21], v[32:33], v[22:23]
	v_pk_mul_f32 v[22:23], v[34:35], v[26:27]
	v_mov_b32_e32 v17, v3
	v_or_b32_e32 v16, 0x160, v2
	v_pk_mul_f32 v[26:27], v[36:37], v[28:29]
	v_lshl_add_u64 v[16:17], v[12:13], 0, v[16:17]
	s_waitcnt vmcnt(30)
	v_mul_f32_e32 v4, v124, v6
	v_mul_f32_e32 v6, v125, v20
	v_mul_f32_e32 v8, v126, v22
	v_mul_f32_e32 v9, v127, v26
	v_mul_f32_e32 v4, v4, v7
	v_mul_f32_e32 v6, v6, v21
	v_mul_f32_e32 v7, v8, v23
	v_mul_f32_e32 v8, v9, v27
	v_cvt_pk_bf16_f32 v6, v4, v6
	v_cvt_pk_bf16_f32 v7, v7, v8
	global_store_dwordx2 v[16:17], v[6:7], off
	ds_read2_b64 v[20:23], v109 offset0:48 offset1:52
	v_mov_b32_e32 v17, v3
	v_or_b32_e32 v16, 0x180, v2
	v_lshl_add_u64 v[14:15], v[12:13], 0, v[16:17]
	s_waitcnt lgkmcnt(0)
	v_lshlrev_b32_e32 v30, 16, v21
	v_and_b32_e32 v32, 0xffff0000, v21
	s_waitcnt vmcnt(30)
	v_lshlrev_b32_e32 v17, 16, v132
	v_and_b32_e32 v21, 0xffff0000, v132
	v_lshlrev_b32_e32 v31, 16, v133
	v_and_b32_e32 v33, 0xffff0000, v133
	v_mul_f32_e32 v4, 0xbfb8aa3b, v17
	v_mul_f32_e32 v19, 0xbfb8aa3b, v21
	v_mul_f32_e32 v24, 0xbfb8aa3b, v31
	v_mul_f32_e32 v25, 0xbfb8aa3b, v33
	v_exp_f32_e32 v4, v4
	v_exp_f32_e32 v19, v19
	v_exp_f32_e32 v24, v24
	v_exp_f32_e32 v25, v25
	v_add_f32_e32 v4, 1.0, v4
	v_add_f32_e32 v19, 1.0, v19
	v_add_f32_e32 v24, 1.0, v24
	v_add_f32_e32 v25, 1.0, v25
	v_rcp_f32_e32 v35, v4
	v_rcp_f32_e32 v37, v19
	v_rcp_f32_e32 v39, v24
	v_rcp_f32_e32 v41, v25
	v_lshlrev_b32_e32 v16, 16, v20
	v_and_b32_e32 v20, 0xffff0000, v20
	v_pk_mul_f32 v[16:17], v[34:35], v[16:17]
	v_pk_mul_f32 v[20:21], v[36:37], v[20:21]
	v_pk_mul_f32 v[24:25], v[38:39], v[30:31]
	v_pk_mul_f32 v[30:31], v[40:41], v[32:33]
	v_mov_b32_e32 v32, v5
	s_waitcnt vmcnt(29)
	v_mul_f32_e32 v4, v134, v16
	v_mul_f32_e32 v8, v135, v20
	v_mul_f32_e32 v9, v136, v24
	v_mul_f32_e32 v10, v137, v30
	v_mul_f32_e32 v8, v8, v21
	v_mul_f32_e32 v9, v9, v25
	v_mul_f32_e32 v4, v4, v17
	v_mul_f32_e32 v10, v10, v31
	v_cvt_pk_bf16_f32 v8, v4, v8
	v_cvt_pk_bf16_f32 v9, v9, v10
	global_store_dwordx2 v[14:15], v[8:9], off
	v_lshlrev_b32_e32 v16, 16, v22
	v_and_b32_e32 v20, 0xffff0000, v22
	v_lshlrev_b32_e32 v22, 16, v23
	v_and_b32_e32 v24, 0xffff0000, v23
	s_waitcnt vmcnt(29)
	v_lshlrev_b32_e32 v17, 16, v138
	v_and_b32_e32 v21, 0xffff0000, v138
	v_lshlrev_b32_e32 v23, 16, v139
	v_and_b32_e32 v25, 0xffff0000, v139
	v_mul_f32_e32 v4, 0xbfb8aa3b, v17
	v_mul_f32_e32 v19, 0xbfb8aa3b, v21
	v_mul_f32_e32 v26, 0xbfb8aa3b, v23
	v_mul_f32_e32 v27, 0xbfb8aa3b, v25
	v_exp_f32_e32 v4, v4
	v_exp_f32_e32 v19, v19
	v_exp_f32_e32 v26, v26
	v_exp_f32_e32 v27, v27
	v_add_f32_e32 v4, 1.0, v4
	v_add_f32_e32 v19, 1.0, v19
	v_add_f32_e32 v26, 1.0, v26
	v_add_f32_e32 v27, 1.0, v27
	v_rcp_f32_e32 v31, v4
	v_rcp_f32_e32 v33, v19
	v_rcp_f32_e32 v35, v26
	v_rcp_f32_e32 v37, v27
	v_mov_b32_e32 v30, v5
	v_pk_mul_f32 v[16:17], v[30:31], v[16:17]
	v_pk_mul_f32 v[20:21], v[32:33], v[20:21]
	v_pk_mul_f32 v[22:23], v[34:35], v[22:23]
	v_mov_b32_e32 v15, v3
	v_or_b32_e32 v14, 0x1a0, v2
	v_pk_mul_f32 v[24:25], v[36:37], v[24:25]
	v_lshl_add_u64 v[14:15], v[12:13], 0, v[14:15]
	s_waitcnt vmcnt(28)
	v_and_b32_e32 v27, 0xffff0000, v141
	s_waitcnt vmcnt(26)
	v_mul_f32_e32 v4, v144, v16
	v_mul_f32_e32 v8, v145, v20
	v_mul_f32_e32 v9, v146, v22
	v_mul_f32_e32 v10, v147, v24
	v_mul_f32_e32 v8, v8, v21
	v_mul_f32_e32 v9, v9, v23
	v_mul_f32_e32 v4, v4, v17
	v_mul_f32_e32 v10, v10, v25
	v_cvt_pk_bf16_f32 v8, v4, v8
	v_cvt_pk_bf16_f32 v9, v9, v10
	global_store_dwordx2 v[14:15], v[8:9], off
	ds_read2_b64 v[14:17], v109 offset0:56 offset1:60
	v_lshlrev_b32_e32 v23, 16, v140
	v_lshlrev_b32_e32 v25, 16, v141
	v_mul_f32_e32 v4, 0xbfb8aa3b, v23
	v_mul_f32_e32 v29, 0xbfb8aa3b, v27
	s_waitcnt lgkmcnt(0)
	v_lshlrev_b32_e32 v24, 16, v15
	v_and_b32_e32 v26, 0xffff0000, v15
	v_and_b32_e32 v15, 0xffff0000, v140
	v_mul_f32_e32 v19, 0xbfb8aa3b, v15
	v_mul_f32_e32 v28, 0xbfb8aa3b, v25
	v_exp_f32_e32 v4, v4
	v_exp_f32_e32 v19, v19
	v_exp_f32_e32 v28, v28
	v_exp_f32_e32 v29, v29
	v_add_f32_e32 v4, 1.0, v4
	v_add_f32_e32 v19, 1.0, v19
	v_add_f32_e32 v28, 1.0, v28
	v_add_f32_e32 v29, 1.0, v29
	v_rcp_f32_e32 v31, v4
	v_rcp_f32_e32 v33, v19
	v_rcp_f32_e32 v35, v28
	v_rcp_f32_e32 v37, v29
	v_lshlrev_b32_e32 v22, 16, v14
	v_and_b32_e32 v14, 0xffff0000, v14
	v_pk_mul_f32 v[22:23], v[30:31], v[22:23]
	v_pk_mul_f32 v[14:15], v[32:33], v[14:15]
	v_pk_mul_f32 v[24:25], v[34:35], v[24:25]
	v_mov_b32_e32 v21, v3
	v_or_b32_e32 v20, 0x1c0, v2
	v_pk_mul_f32 v[26:27], v[36:37], v[26:27]
	v_lshl_add_u64 v[20:21], v[12:13], 0, v[20:21]
	v_or_b32_e32 v2, 0x1e0, v2
	v_mov_b32_e32 v28, v5
	v_lshlrev_b32_e32 v19, 16, v143
	v_lshl_add_u64 v[12:13], v[12:13], 0, v[2:3]
	v_mov_b32_e32 v30, v0
	s_waitcnt vmcnt(26)
	v_mul_f32_e32 v4, v148, v22
	v_mul_f32_e32 v8, v149, v14
	v_mul_f32_e32 v9, v150, v24
	v_mul_f32_e32 v10, v151, v26
	v_mul_f32_e32 v8, v8, v15
	v_mul_f32_e32 v9, v9, v25
	v_mul_f32_e32 v4, v4, v23
	v_mul_f32_e32 v10, v10, v27
	v_cvt_pk_bf16_f32 v8, v4, v8
	v_cvt_pk_bf16_f32 v9, v9, v10
	global_store_dwordx2 v[20:21], v[8:9], off
	v_lshlrev_b32_e32 v18, 16, v17
	v_and_b32_e32 v20, 0xffff0000, v17
	v_mov_b32_e32 v22, v5
	v_mov_b32_e32 v24, v5
	v_mov_b32_e32 v26, v5
	v_lshlrev_b32_e32 v5, 16, v142
	v_and_b32_e32 v17, 0xffff0000, v142
	v_and_b32_e32 v21, 0xffff0000, v143
	v_mul_f32_e32 v2, 0xbfb8aa3b, v5
	v_mul_f32_e32 v6, 0xbfb8aa3b, v17
	v_mul_f32_e32 v7, 0xbfb8aa3b, v19
	v_mul_f32_e32 v23, 0xbfb8aa3b, v21
	v_exp_f32_e32 v2, v2
	v_exp_f32_e32 v6, v6
	v_exp_f32_e32 v7, v7
	v_exp_f32_e32 v23, v23
	v_add_f32_e32 v2, 1.0, v2
	v_add_f32_e32 v6, 1.0, v6
	v_add_f32_e32 v7, 1.0, v7
	v_add_f32_e32 v29, 1.0, v23
	v_rcp_f32_e32 v23, v2
	v_rcp_f32_e32 v25, v6
	v_rcp_f32_e32 v27, v7
	v_rcp_f32_e32 v29, v29
	v_lshlrev_b32_e32 v4, 16, v16
	v_and_b32_e32 v16, 0xffff0000, v16
	v_pk_mul_f32 v[4:5], v[22:23], v[4:5]
	v_pk_mul_f32 v[6:7], v[24:25], v[16:17]
	v_pk_mul_f32 v[16:17], v[26:27], v[18:19]
	v_pk_mul_f32 v[18:19], v[28:29], v[20:21]
	v_mov_b64_e32 v[14:15], s[88:89]
	s_waitcnt vmcnt(26)
	v_mul_f32_e32 v2, v152, v4
	v_mul_f32_e32 v4, v153, v6
	v_mul_f32_e32 v6, v154, v16
	v_mul_f32_e32 v8, v155, v18
	v_mul_f32_e32 v2, v2, v5
	v_mul_f32_e32 v4, v4, v7
	v_mul_f32_e32 v5, v6, v17
	v_mul_f32_e32 v6, v8, v19
	v_cvt_pk_bf16_f32 v4, v2, v4
	v_cvt_pk_bf16_f32 v5, v5, v6
	global_store_dwordx2 v[12:13], v[4:5], off
	s_nop 0
	v_and_b32_e32 v52, 15, v30
	v_ashrrev_i32_e32 v2, 6, v30
	v_or_b32_e32 v5, s20, v52
	v_ashrrev_i32_e32 v46, 1, v30
	v_lshl_add_u32 v116, v2, 4, v5
	v_lshl_add_u32 v4, s0, 8, v46
	v_mad_i64_i32 v[118:119], s[0:1], v116, s92, v[14:15]
	v_ashrrev_i32_e32 v5, 31, v4
	v_readlane_b32 s0, v244, 50
	v_and_b32_e32 v50, 1, v30
	v_lshlrev_b64 v[4:5], 10, v[4:5]
	v_readlane_b32 s1, v244, 51
	v_bfe_u32 v47, v30, 4, 2
	v_lshlrev_b32_e32 v44, 6, v50
	v_lshl_add_u64 v[4:5], s[0:1], 0, v[4:5]
	v_lshlrev_b32_e32 v114, 4, v47
	v_lshl_add_u64 v[20:21], v[4:5], 0, v[44:45]
	v_lshl_add_u64 v[120:121], v[118:119], 0, v[114:115]
	s_waitcnt vmcnt(16)
	v_and_b32_e32 v108, 63, v0
	v_lshlrev_b32_e32 v108, 2, v108
	v_add_u32_e32 v108, 0x21c00, v108
	ds_write_b32 v108, v195
	s_waitcnt lgkmcnt(0)
	v_mov_b64_e32 v[4:5], v[156:157]
	v_mov_b64_e32 v[6:7], v[158:159]
	v_mov_b64_e32 v[12:13], v[160:161]
	v_mov_b64_e32 v[14:15], v[162:163]
	v_mov_b64_e32 v[16:17], v[164:165]
	v_mov_b64_e32 v[18:19], v[166:167]
	v_mov_b64_e32 v[8:9], v[172:173]
	v_mov_b64_e32 v[10:11], v[174:175]
	v_mov_b64_e32 v[28:29], v[176:177]
	v_mov_b64_e32 v[30:31], v[178:179]
	v_mov_b64_e32 v[32:33], v[196:197]
	v_mov_b64_e32 v[34:35], v[198:199]
	v_mov_b64_e32 v[36:37], v[200:201]
	v_mov_b64_e32 v[38:39], v[202:203]
	v_mov_b64_e32 v[40:41], v[204:205]
	v_mov_b64_e32 v[42:43], v[206:207]
	s_nop 0
	v_mov_b64_e32 v[20:21], v[208:209]
	v_mov_b64_e32 v[22:23], v[210:211]
	v_mov_b64_e32 v[24:25], v[212:213]
	v_mov_b64_e32 v[26:27], v[214:215]
	v_readlane_b32 s0, v243, 0
	v_mul_lo_u32 v45, v46, s97
	s_and_b32 s0, s0, 7
	v_add_u32_e32 v48, 0, v45
	s_lshl_b32 s2, s0, 18
	v_add_u32_e32 v132, v48, v44
	v_mad_u64_u32 v[48:49], s[0:1], v46, s98, v[48:49]
	v_mul_u32_u24_e32 v45, 0x4200, v50
	v_lshlrev_b32_e32 v50, 7, v50
	v_mul_lo_u32 v131, v2, s93
	v_lshlrev_b32_e32 v2, 3, v47
	v_add_u32_e32 v122, 0x21c00, v50
	v_lshlrev_b32_e32 v50, 5, v47
	v_or_b32_e32 v47, 16, v52
	s_movk_i32 s0, 0x210
	v_lshl_add_u64 v[124:125], s[8:9], 0, v[50:51]
	global_load_dwordx4 v[224:227], v[124:125], off
	global_load_dwordx4 v[228:231], v[124:125], off offset:128
	global_load_dwordx4 v[232:235], v[124:125], off offset:16
	global_load_dwordx4 v[236:239], v[124:125], off offset:144
	v_mul_u32_u24_e32 v51, 0x210, v47
	v_mad_u32_u24 v47, v52, s0, v131
	v_add3_u32 v134, v47, v2, s96
	v_ashrrev_i32_e32 v47, 31, v46
	v_lshlrev_b64 v[46:47], 10, v[46:47]
	v_add_u32_e32 v49, 0, v114
	s_mov_b32 s1, s3
	v_lshl_add_u64 v[46:47], s[2:3], 0, v[46:47]
	v_mov_b32_e32 v133, v49
	v_mul_u32_u24_e32 v50, 0x90, v52
	v_writelane_b32 v244, s0, 62
	v_or_b32_e32 v46, v46, v44
	v_mul_u32_u24_e32 v115, 0x210, v52
	v_ashrrev_i32_e32 v117, 31, v116
	v_writelane_b32 v244, s1, 63
	v_lshl_add_u64 v[126:127], s[6:7], 0, v[46:47]
	s_mov_b64 s[0:1], 64
	v_and_b32_e32 v241, 24, v48
	v_and_b32_e32 v242, 32, v48
	v_and_b32_e32 v48, 0xffffffc7, v48
	v_lshlrev_b32_e32 v241, 1, v241
	v_lshrrev_b32_e32 v242, 2, v242
	v_or3_b32 v48, v48, v241, v242
	v_add_u32_e32 v135, v48, v45
	v_add_u32_e32 v136, v49, v50
	v_add_u32_e32 v137, v133, v51
	v_add_u32_e32 v240, v133, v115
	v_add_u32_e32 v240, 0x9000, v240
	v_add_u32_e32 v241, 0x9000, v137
	v_add_u32_e32 v242, 0xb000, v137
	v_add_u32_e32 v245, 0xd000, v137
	s_branch .LBB0_210

.LBB0_210:
	s_barrier
	ds_read_b128 v[44:47], v122 offset:16
	ds_read_b128 v[60:63], v122
	ds_read_b128 v[52:55], v122 offset:48
	ds_read_b128 v[56:59], v122 offset:32
	ds_read_b128 v[48:51], v122 offset:80
	ds_read_b128 v[72:75], v122 offset:64
	ds_read_b128 v[64:67], v122 offset:112
	ds_read_b128 v[68:71], v122 offset:96
	s_waitcnt vmcnt(0)
	v_and_b32_e32 v83, 0xffff0000, v8
	v_lshlrev_b32_e32 v84, 16, v8
	v_mul_f32_e32 v96, v83, v83
	v_lshlrev_b32_e32 v82, 16, v9
	v_fmac_f32_e32 v96, v84, v84
	v_and_b32_e32 v81, 0xffff0000, v9
	v_fmac_f32_e32 v96, v82, v82
	v_lshlrev_b32_e32 v80, 16, v10
	v_fmac_f32_e32 v96, v81, v81
	v_and_b32_e32 v98, 0xffff0000, v10
	v_fmac_f32_e32 v96, v80, v80
	v_lshlrev_b32_e32 v99, 16, v11
	v_fmac_f32_e32 v96, v98, v98
	v_and_b32_e32 v100, 0xffff0000, v11
	v_fmac_f32_e32 v96, v99, v99
	v_lshlrev_b32_e32 v101, 16, v16
	v_fmac_f32_e32 v96, v100, v100
	v_and_b32_e32 v102, 0xffff0000, v16
	v_fmac_f32_e32 v96, v101, v101
	v_lshlrev_b32_e32 v103, 16, v17
	v_fmac_f32_e32 v96, v102, v102
	v_and_b32_e32 v104, 0xffff0000, v17
	v_fmac_f32_e32 v96, v103, v103
	v_lshlrev_b32_e32 v105, 16, v18
	v_fmac_f32_e32 v96, v104, v104
	v_and_b32_e32 v106, 0xffff0000, v18
	v_fmac_f32_e32 v96, v105, v105
	v_lshlrev_b32_e32 v107, 16, v19
	v_fmac_f32_e32 v96, v106, v106
	v_and_b32_e32 v108, 0xffff0000, v19
	v_fmac_f32_e32 v96, v107, v107
	v_lshlrev_b32_e32 v109, 16, v12
	v_fmac_f32_e32 v96, v108, v108
	v_and_b32_e32 v94, 0xffff0000, v12
	v_fmac_f32_e32 v96, v109, v109
	v_lshlrev_b32_e32 v92, 16, v13
	v_fmac_f32_e32 v96, v94, v94
	v_and_b32_e32 v95, 0xffff0000, v13
	v_fmac_f32_e32 v96, v92, v92
	v_lshlrev_b32_e32 v93, 16, v14
	v_fmac_f32_e32 v96, v95, v95
	v_and_b32_e32 v91, 0xffff0000, v14
	v_fmac_f32_e32 v96, v93, v93
	v_lshlrev_b32_e32 v90, 16, v15
	v_fmac_f32_e32 v96, v91, v91
	v_and_b32_e32 v89, 0xffff0000, v15
	v_fmac_f32_e32 v96, v90, v90
	v_lshlrev_b32_e32 v88, 16, v4
	v_fmac_f32_e32 v96, v89, v89
	v_and_b32_e32 v87, 0xffff0000, v4
	v_fmac_f32_e32 v96, v88, v88
	v_lshlrev_b32_e32 v86, 16, v5
	v_fmac_f32_e32 v96, v87, v87
	v_and_b32_e32 v85, 0xffff0000, v5
	v_fmac_f32_e32 v96, v86, v86
	v_and_b32_e32 v76, 0xffff0000, v6
	v_lshlrev_b32_e32 v77, 16, v6
	v_fmac_f32_e32 v96, v85, v85
	v_pk_mul_f32 v[78:79], v[76:77], v[76:77]
	s_cmpk_lg_i32 s4, 0x180
	v_add_f32_e32 v79, v79, v96
	v_add_f32_e32 v110, v78, v79
	v_and_b32_e32 v78, 0xffff0000, v7
	v_lshlrev_b32_e32 v79, 16, v7
	v_pk_mul_f32 v[96:97], v[78:79], v[78:79]
	s_cselect_b64 s[2:3], -1, 0
	v_add_f32_e32 v97, v97, v110
	v_add_f32_e32 v96, v96, v97
	s_nop 1
	s_cmpk_eq_i32 s4, 0x180
	s_waitcnt lgkmcnt(0)
	v_add_f32_dpp v96, v96, v96 quad_perm:[1,0,3,2] row_mask:0xf bank_mask:0xf
	v_fmamk_f32 v96, v96, 0x3c800000, v180
	v_rsq_f32_e32 v96, v96
	s_nop 0
	v_mul_f32_e32 v80, v96, v80
	v_mul_f32_e32 v81, v96, v81
	v_mul_f32_e32 v80, v44, v80
	v_mul_f32_e32 v44, v96, v98
	v_mul_f32_e32 v82, v96, v82
	v_mul_f32_e32 v63, v63, v81
	v_mul_f32_e32 v81, v45, v44
	v_mul_f32_e32 v44, v96, v99
	v_mul_f32_e32 v62, v62, v82
	v_mul_f32_e32 v82, v46, v44
	v_mul_f32_e32 v44, v96, v100
	v_mul_f32_e32 v47, v47, v44
	v_mul_f32_e32 v44, v96, v101
	v_mul_f32_e32 v56, v56, v44
	v_mul_f32_e32 v44, v96, v102
	v_mul_f32_e32 v57, v57, v44
	v_mul_f32_e32 v44, v96, v103
	v_mul_f32_e32 v58, v58, v44
	v_mul_f32_e32 v44, v96, v104
	v_mul_f32_e32 v59, v59, v44
	v_mul_f32_e32 v44, v96, v105
	v_mul_f32_e32 v52, v52, v44
	v_mul_f32_e32 v44, v96, v106
	v_mul_f32_e32 v53, v53, v44
	v_mul_f32_e32 v44, v96, v107
	v_mul_f32_e32 v54, v54, v44
	v_mul_f32_e32 v44, v96, v108
	v_mul_f32_e32 v55, v55, v44
	v_mul_f32_e32 v44, v96, v109
	v_mul_f32_e32 v72, v72, v44
	v_mul_f32_e32 v44, v96, v94
	v_mul_f32_e32 v73, v73, v44
	v_mul_f32_e32 v44, v96, v92
	v_mul_f32_e32 v74, v74, v44
	v_mul_f32_e32 v44, v96, v95
	v_mul_f32_e32 v75, v75, v44
	v_mul_f32_e32 v44, v96, v93
	v_mul_f32_e32 v48, v48, v44
	v_mul_f32_e32 v44, v96, v91
	v_mul_f32_e32 v49, v49, v44
	v_mul_f32_e32 v44, v96, v90
	v_mul_f32_e32 v50, v50, v44
	v_mul_f32_e32 v44, v96, v89
	v_mul_f32_e32 v51, v51, v44
	v_mul_f32_e32 v44, v96, v88
	s_cmp_eq_u32 s4, 0
	s_cbranch_scc0 .Lxg_skip
	v_bfe_u32 v129, v0, 4, 2
	v_mul_u32_u24_e32 v171, 0x1200, v116
	v_lshl_add_u32 v129, v129, 3, v171
	v_add_u32_e32 v129, 0x1000, v129
	global_load_dwordx2 v[150:151], v129, s[88:89]
	global_load_dwordx2 v[152:153], v129, s[88:89] offset:32
	global_load_dwordx2 v[154:155], v129, s[88:89] offset:64
	global_load_dwordx2 v[156:157], v129, s[88:89] offset:96
	global_load_dwordx2 v[158:159], v129, s[88:89] offset:128
	global_load_dwordx2 v[160:161], v129, s[88:89] offset:160
	global_load_dwordx2 v[162:163], v129, s[88:89] offset:192
	global_load_dwordx2 v[164:165], v129, s[88:89] offset:224
	global_load_dwordx2 v[166:167], v129, s[88:89] offset:256
	global_load_dwordx2 v[168:169], v129, s[88:89] offset:288
	global_load_dwordx2 v[248:249], v129, s[88:89] offset:320
	global_load_dwordx2 v[250:251], v129, s[88:89] offset:352
	global_load_dwordx2 v[252:253], v129, s[88:89] offset:384
	global_load_dwordx2 v[254:255], v129, s[88:89] offset:416
.Lxg_skip:
	s_cmpk_eq_i32 s4, 0x180
	v_mul_f32_e32 v68, v68, v44
	v_mul_f32_e32 v44, v96, v87
	v_mul_f32_e32 v69, v69, v44
	v_mul_f32_e32 v44, v96, v86
	v_mul_f32_e32 v70, v44, v70
	v_mul_f32_e32 v44, v96, v85
	v_mul_f32_e32 v71, v44, v71
	v_mul_f32_e32 v44, v96, v77
	v_mul_f32_e32 v64, v44, v64
	v_mul_f32_e32 v44, v96, v76
	v_mul_f32_e32 v65, v44, v65
	v_mul_f32_e32 v44, v96, v79
	v_mul_f32_e32 v84, v96, v84
	v_mul_f32_e32 v83, v96, v83
	v_mul_f32_e32 v66, v44, v66
	v_mul_f32_e32 v44, v96, v78
	v_mul_f32_e32 v60, v60, v84
	v_mul_f32_e32 v61, v61, v83
	v_mul_f32_e32 v67, v44, v67
	v_cvt_pk_bf16_f32 v44, v60, v61
	v_cvt_pk_bf16_f32 v45, v62, v63
	v_cvt_pk_bf16_f32 v46, v80, v81
	v_cvt_pk_bf16_f32 v47, v82, v47
	ds_write_b128 v132, v[44:47]
	v_cvt_pk_bf16_f32 v44, v56, v57
	v_cvt_pk_bf16_f32 v45, v58, v59
	v_cvt_pk_bf16_f32 v46, v52, v53
	v_cvt_pk_bf16_f32 v47, v54, v55
	ds_write_b128 v132, v[44:47] offset:16
	v_cvt_pk_bf16_f32 v44, v72, v73
	v_cvt_pk_bf16_f32 v45, v74, v75
	v_cvt_pk_bf16_f32 v46, v48, v49
	v_cvt_pk_bf16_f32 v47, v50, v51
	ds_write_b128 v132, v[44:47] offset:32
	v_cvt_pk_bf16_f32 v44, v68, v69
	v_cvt_pk_bf16_f32 v45, v70, v71
	v_cvt_pk_bf16_f32 v46, v64, v65
	v_cvt_pk_bf16_f32 v47, v66, v67
	ds_write_b128 v132, v[44:47] offset:48
	ds_write_b16 v135, v28 offset:36864
	ds_write_b16_d16_hi v135, v28 offset:37392
	ds_write_b16 v135, v29 offset:37920
	ds_write_b16_d16_hi v135, v29 offset:38448
	ds_write_b16 v135, v30 offset:38976
	ds_write_b16_d16_hi v135, v30 offset:39504
	ds_write_b16 v135, v31 offset:40032
	ds_write_b16_d16_hi v135, v31 offset:40560
	ds_write_b16 v135, v32 offset:41088
	ds_write_b16_d16_hi v135, v32 offset:41616
	ds_write_b16 v135, v33 offset:42144
	ds_write_b16_d16_hi v135, v33 offset:42672
	ds_write_b16 v135, v34 offset:43200
	ds_write_b16_d16_hi v135, v34 offset:43728
	ds_write_b16 v135, v35 offset:44256
	ds_write_b16_d16_hi v135, v35 offset:44784
	ds_write_b16 v135, v36 offset:45312
	ds_write_b16_d16_hi v135, v36 offset:45840
	ds_write_b16 v135, v37 offset:46368
	ds_write_b16_d16_hi v135, v37 offset:46896
	ds_write_b16 v135, v38 offset:47424
	ds_write_b16_d16_hi v135, v38 offset:47952
	ds_write_b16 v135, v39 offset:48480
	ds_write_b16_d16_hi v135, v39 offset:49008
	ds_write_b16 v135, v40 offset:49536
	ds_write_b16_d16_hi v135, v40 offset:50064
	ds_write_b16 v135, v41 offset:50592
	ds_write_b16_d16_hi v135, v41 offset:51120
	ds_write_b16 v135, v42 offset:51648
	ds_write_b16_d16_hi v135, v42 offset:52176
	ds_write_b16 v135, v43 offset:52704
	ds_write_b16_d16_hi v135, v43 offset:53232
	s_waitcnt lgkmcnt(0)
	s_barrier
	s_cbranch_scc1 .LBB0_212
	v_lshl_add_u64 v[4:5], v[126:127], 0, s[4:5]
	s_mov_b64 s[6:7], 0xdbe0080
	v_add_co_u32_e32 v40, vcc, 0xdbe0000, v4
	v_lshl_add_u64 v[16:17], v[4:5], 0, s[6:7]
	s_nop 0
	v_addc_co_u32_e32 v41, vcc, 0, v5, vcc
	global_load_dwordx4 v[8:11], v[40:41], off offset:128
	global_load_dwordx4 v[4:7], v[16:17], off offset:48
	global_load_dwordx4 v[12:15], v[16:17], off offset:32
	s_nop 0
	global_load_dwordx4 v[16:19], v[16:17], off offset:16
	s_nop 0
	global_load_dwordx4 v[28:31], v[40:41], off offset:640
	global_load_dwordx4 v[32:35], v[40:41], off offset:656
	global_load_dwordx4 v[36:39], v[40:41], off offset:672
	s_nop 0
	global_load_dwordx4 v[40:43], v[40:41], off offset:688
	s_mov_b64 s[6:7], s[0:1]
	s_branch .LBB0_213
